# sample-row thin GEMMs (G1 Z-proj, G3 SwiGLU) hand-written: staged through LDS by LDS-DMA reading whole 128-B lines, 3-stage ring per wave, adjacent tasks per workgroup; static LDS +8 KiB
# speedup vs baseline: 1.0763x; 1.0359x over previous
.LBB0_143:
	s_andn2_b64 vcc, exec, s[2:3]
	s_cbranch_vccnz .LBB0_148
	v_readlane_b32 s2, v253, 7
	v_readlane_b32 s3, v253, 8
	s_andn2_b64 vcc, exec, s[2:3]
	s_cbranch_vccnz .LBB0_148
	v_readlane_b32 s3, v253, 11
	s_mul_i32 s2, s3, 5
	s_add_i32 s3, s2, 5
	s_min_i32 s3, s3, 0x260
	s_add_i32 s2, s2, s89
	s_cmp_ge_i32 s2, s3
	s_cbranch_scc1 .LBB0_148
	v_and_b32_e32 v175, 63, v12
	v_and_b32_e32 v174, 15, v13
	v_lshrrev_b32_e32 v4, 2, v175
	v_and_b32_e32 v4, 12, v4
	v_lshlrev_b32_e32 v4, 1, v4
	v_bfe_u32 v6, v175, 2, 3
	v_and_b32_e32 v7, 3, v175
	v_lshrrev_b32_e32 v8, 5, v175
	v_lshlrev_b32_e32 v8, 6, v8
	v_lshrrev_b32_e32 v9, 2, v6
	v_sub_u32_e32 v10, 0, v9
	v_and_b32_e32 v10, 3, v10
	v_xor_b32_e32 v10, v10, v7
	v_lshl_or_b32 v1, v10, 4, v8
	v_lshl_or_b32 v1, v6, 11, v1
	v_sub_u32_e32 v10, 2, v9
	v_and_b32_e32 v10, 3, v10
	v_xor_b32_e32 v10, v10, v7
	v_lshl_or_b32 v2, v10, 4, v8
	v_add_u32_e32 v6, 8, v6
	v_lshl_or_b32 v2, v6, 11, v2
	v_lshrrev_b32_e32 v6, 4, v175
	v_lshrrev_b32_e32 v7, 2, v174
	v_sub_u32_e32 v7, 0, v7
	v_and_b32_e32 v7, 3, v7
	v_xor_b32_e32 v6, v6, v7
	v_lshlrev_b32_e32 v6, 4, v6
	v_and_b32_e32 v7, 7, v174
	v_lshl_or_b32 v6, v7, 6, v6
	v_lshrrev_b32_e32 v7, 3, v174
	v_lshl_or_b32 v6, v7, 10, v6
	s_mul_i32 s21, s89, 0x4800
	v_add_u32_e32 v0, s21, v6
	v_readlane_b32 s14, v255, 31
	v_readlane_b32 s15, v255, 32
	s_add_u32 s16, s8, 0x2000000
	s_addc_u32 s17, s9, 0
	s_waitcnt vmcnt(0) lgkmcnt(0)
.Lthinz_task:
	s_and_b32 s7, s2, 7
	s_lshl_b32 s7, s7, 4
	s_lshr_b32 s12, s2, 3
	s_lshl_b32 s13, s12, 6
	s_lshl_b32 s12, s12, 16
	s_lshl_b32 s6, s7, 11
	s_add_u32 s8, s14, s12
	s_addc_u32 s9, s15, 0
	s_add_u32 s10, s8, 0x8000
	s_addc_u32 s11, s9, 0
	s_add_u32 s6, s16, s6
	s_mov_b32 s12, s7
	s_addc_u32 s7, s17, 0
	v_or_b32_e32 v13, s12, v174
	v_or_b32_e32 v12, 0x4000, v13
	v_lshlrev_b32_e32 v194, 3, v12
	v_lshl_add_u64 v[14:15], s[4:5], 0, v[194:195]
	global_load_dwordx2 v[14:15], v[14:15], off
	v_mov_b32_e32 v3, v1
	v_mov_b32_e32 v5, v2
	s_add_i32 m0, s21, 0x0
	s_nop 0
	global_load_lds_dwordx4 v3, s[6:7]
	s_add_i32 m0, s21, 0x400
	s_nop 0
	global_load_lds_dwordx4 v5, s[6:7]
	s_add_i32 m0, s21, 0x800
	s_nop 0
	global_load_lds_dwordx4 v3, s[8:9]
	s_add_i32 m0, s21, 0xc00
	s_nop 0
	global_load_lds_dwordx4 v5, s[8:9]
	s_add_i32 m0, s21, 0x1000
	s_nop 0
	global_load_lds_dwordx4 v3, s[10:11]
	s_add_i32 m0, s21, 0x1400
	s_nop 0
	global_load_lds_dwordx4 v5, s[10:11]
	v_add_u32_e32 v3, 0x80, v3
	v_add_u32_e32 v5, 0x80, v5
	s_add_i32 m0, s21, 0x1800
	s_nop 0
	global_load_lds_dwordx4 v3, s[6:7]
	s_add_i32 m0, s21, 0x1c00
	s_nop 0
	global_load_lds_dwordx4 v5, s[6:7]
	s_add_i32 m0, s21, 0x2000
	s_nop 0
	global_load_lds_dwordx4 v3, s[8:9]
	s_add_i32 m0, s21, 0x2400
	s_nop 0
	global_load_lds_dwordx4 v5, s[8:9]
	s_add_i32 m0, s21, 0x2800
	s_nop 0
	global_load_lds_dwordx4 v3, s[10:11]
	s_add_i32 m0, s21, 0x2c00
	s_nop 0
	global_load_lds_dwordx4 v5, s[10:11]
	v_add_u32_e32 v3, 0x80, v3
	v_add_u32_e32 v5, 0x80, v5
	s_add_i32 m0, s21, 0x3000
	s_nop 0
	global_load_lds_dwordx4 v3, s[6:7]
	s_add_i32 m0, s21, 0x3400
	s_nop 0
	global_load_lds_dwordx4 v5, s[6:7]
	s_add_i32 m0, s21, 0x3800
	s_nop 0
	global_load_lds_dwordx4 v3, s[8:9]
	s_add_i32 m0, s21, 0x3c00
	s_nop 0
	global_load_lds_dwordx4 v5, s[8:9]
	s_add_i32 m0, s21, 0x4000
	s_nop 0
	global_load_lds_dwordx4 v3, s[10:11]
	s_add_i32 m0, s21, 0x4400
	s_nop 0
	global_load_lds_dwordx4 v5, s[10:11]
	v_add_u32_e32 v3, 0x80, v3
	v_add_u32_e32 v5, 0x80, v5
	s_waitcnt vmcnt(12)
	ds_read_b128 v[28:31], v0 offset:0
	ds_read_b128 v[36:39], v0 offset:2048
	ds_read_b128 v[44:47], v0 offset:4096
	ds_read_b128 v[32:35], v0 offset:512
	ds_read_b128 v[40:43], v0 offset:2560
	ds_read_b128 v[48:51], v0 offset:4608
	s_waitcnt lgkmcnt(0)
	s_add_i32 m0, s21, 0x0
	v_mfma_f32_16x16x32_bf16 v[20:23], v[36:39], v[28:31], 0
	global_load_lds_dwordx4 v3, s[6:7]
	s_add_i32 m0, s21, 0x400
	v_mfma_f32_16x16x32_bf16 v[24:27], v[44:47], v[28:31], 0
	global_load_lds_dwordx4 v5, s[6:7]
	s_add_i32 m0, s21, 0x800
	v_mfma_f32_16x16x32_bf16 v[20:23], v[40:43], v[32:35], v[20:23]
	global_load_lds_dwordx4 v3, s[8:9]
	s_add_i32 m0, s21, 0xc00
	v_mfma_f32_16x16x32_bf16 v[24:27], v[48:51], v[32:35], v[24:27]
	global_load_lds_dwordx4 v5, s[8:9]
	s_add_i32 m0, s21, 0x1000
	s_nop 0
	global_load_lds_dwordx4 v3, s[10:11]
	s_add_i32 m0, s21, 0x1400
	s_nop 0
	global_load_lds_dwordx4 v5, s[10:11]
	v_add_u32_e32 v3, 0x80, v3
	v_add_u32_e32 v5, 0x80, v5
	s_waitcnt vmcnt(12)
	ds_read_b128 v[28:31], v0 offset:6144
	ds_read_b128 v[36:39], v0 offset:8192
	ds_read_b128 v[44:47], v0 offset:10240
	ds_read_b128 v[32:35], v0 offset:6656
	ds_read_b128 v[40:43], v0 offset:8704
	ds_read_b128 v[48:51], v0 offset:10752
	s_waitcnt lgkmcnt(0)
	s_add_i32 m0, s21, 0x1800
	v_mfma_f32_16x16x32_bf16 v[20:23], v[36:39], v[28:31], v[20:23]
	global_load_lds_dwordx4 v3, s[6:7]
	s_add_i32 m0, s21, 0x1c00
	v_mfma_f32_16x16x32_bf16 v[24:27], v[44:47], v[28:31], v[24:27]
	global_load_lds_dwordx4 v5, s[6:7]
	s_add_i32 m0, s21, 0x2000
	v_mfma_f32_16x16x32_bf16 v[20:23], v[40:43], v[32:35], v[20:23]
	global_load_lds_dwordx4 v3, s[8:9]
	s_add_i32 m0, s21, 0x2400
	v_mfma_f32_16x16x32_bf16 v[24:27], v[48:51], v[32:35], v[24:27]
	global_load_lds_dwordx4 v5, s[8:9]
	s_add_i32 m0, s21, 0x2800
	s_nop 0
	global_load_lds_dwordx4 v3, s[10:11]
	s_add_i32 m0, s21, 0x2c00
	s_nop 0
	global_load_lds_dwordx4 v5, s[10:11]
	v_add_u32_e32 v3, 0x80, v3
	v_add_u32_e32 v5, 0x80, v5
	s_waitcnt vmcnt(12)
	ds_read_b128 v[28:31], v0 offset:12288
	ds_read_b128 v[36:39], v0 offset:14336
	ds_read_b128 v[44:47], v0 offset:16384
	ds_read_b128 v[32:35], v0 offset:12800
	ds_read_b128 v[40:43], v0 offset:14848
	ds_read_b128 v[48:51], v0 offset:16896
	s_waitcnt lgkmcnt(0)
	s_add_i32 m0, s21, 0x3000
	v_mfma_f32_16x16x32_bf16 v[20:23], v[36:39], v[28:31], v[20:23]
	global_load_lds_dwordx4 v3, s[6:7]
	s_add_i32 m0, s21, 0x3400
	v_mfma_f32_16x16x32_bf16 v[24:27], v[44:47], v[28:31], v[24:27]
	global_load_lds_dwordx4 v5, s[6:7]
	s_add_i32 m0, s21, 0x3800
	v_mfma_f32_16x16x32_bf16 v[20:23], v[40:43], v[32:35], v[20:23]
	global_load_lds_dwordx4 v3, s[8:9]
	s_add_i32 m0, s21, 0x3c00
	v_mfma_f32_16x16x32_bf16 v[24:27], v[48:51], v[32:35], v[24:27]
	global_load_lds_dwordx4 v5, s[8:9]
	s_add_i32 m0, s21, 0x4000
	s_nop 0
	global_load_lds_dwordx4 v3, s[10:11]
	s_add_i32 m0, s21, 0x4400
	s_nop 0
	global_load_lds_dwordx4 v5, s[10:11]
	v_add_u32_e32 v3, 0x80, v3
	v_add_u32_e32 v5, 0x80, v5
	s_waitcnt vmcnt(12)
	ds_read_b128 v[28:31], v0 offset:0
	ds_read_b128 v[36:39], v0 offset:2048
	ds_read_b128 v[44:47], v0 offset:4096
	ds_read_b128 v[32:35], v0 offset:512
	ds_read_b128 v[40:43], v0 offset:2560
	ds_read_b128 v[48:51], v0 offset:4608
	s_waitcnt lgkmcnt(0)
	s_add_i32 m0, s21, 0x0
	v_mfma_f32_16x16x32_bf16 v[20:23], v[36:39], v[28:31], v[20:23]
	global_load_lds_dwordx4 v3, s[6:7]
	s_add_i32 m0, s21, 0x400
	v_mfma_f32_16x16x32_bf16 v[24:27], v[44:47], v[28:31], v[24:27]
	global_load_lds_dwordx4 v5, s[6:7]
	s_add_i32 m0, s21, 0x800
	v_mfma_f32_16x16x32_bf16 v[20:23], v[40:43], v[32:35], v[20:23]
	global_load_lds_dwordx4 v3, s[8:9]
	s_add_i32 m0, s21, 0xc00
	v_mfma_f32_16x16x32_bf16 v[24:27], v[48:51], v[32:35], v[24:27]
	global_load_lds_dwordx4 v5, s[8:9]
	s_add_i32 m0, s21, 0x1000
	s_nop 0
	global_load_lds_dwordx4 v3, s[10:11]
	s_add_i32 m0, s21, 0x1400
	s_nop 0
	global_load_lds_dwordx4 v5, s[10:11]
	v_add_u32_e32 v3, 0x80, v3
	v_add_u32_e32 v5, 0x80, v5
	s_waitcnt vmcnt(12)
	ds_read_b128 v[28:31], v0 offset:6144
	ds_read_b128 v[36:39], v0 offset:8192
	ds_read_b128 v[44:47], v0 offset:10240
	ds_read_b128 v[32:35], v0 offset:6656
	ds_read_b128 v[40:43], v0 offset:8704
	ds_read_b128 v[48:51], v0 offset:10752
	s_waitcnt lgkmcnt(0)
	s_add_i32 m0, s21, 0x1800
	v_mfma_f32_16x16x32_bf16 v[20:23], v[36:39], v[28:31], v[20:23]
	global_load_lds_dwordx4 v3, s[6:7]
	s_add_i32 m0, s21, 0x1c00
	v_mfma_f32_16x16x32_bf16 v[24:27], v[44:47], v[28:31], v[24:27]
	global_load_lds_dwordx4 v5, s[6:7]
	s_add_i32 m0, s21, 0x2000
	v_mfma_f32_16x16x32_bf16 v[20:23], v[40:43], v[32:35], v[20:23]
	global_load_lds_dwordx4 v3, s[8:9]
	s_add_i32 m0, s21, 0x2400
	v_mfma_f32_16x16x32_bf16 v[24:27], v[48:51], v[32:35], v[24:27]
	global_load_lds_dwordx4 v5, s[8:9]
	s_add_i32 m0, s21, 0x2800
	s_nop 0
	global_load_lds_dwordx4 v3, s[10:11]
	s_add_i32 m0, s21, 0x2c00
	s_nop 0
	global_load_lds_dwordx4 v5, s[10:11]
	v_add_u32_e32 v3, 0x80, v3
	v_add_u32_e32 v5, 0x80, v5
	s_waitcnt vmcnt(12)
	ds_read_b128 v[28:31], v0 offset:12288
	ds_read_b128 v[36:39], v0 offset:14336
	ds_read_b128 v[44:47], v0 offset:16384
	ds_read_b128 v[32:35], v0 offset:12800
	ds_read_b128 v[40:43], v0 offset:14848
	ds_read_b128 v[48:51], v0 offset:16896
	s_waitcnt lgkmcnt(0)
	s_add_i32 m0, s21, 0x3000
	v_mfma_f32_16x16x32_bf16 v[20:23], v[36:39], v[28:31], v[20:23]
	global_load_lds_dwordx4 v3, s[6:7]
	s_add_i32 m0, s21, 0x3400
	v_mfma_f32_16x16x32_bf16 v[24:27], v[44:47], v[28:31], v[24:27]
	global_load_lds_dwordx4 v5, s[6:7]
	s_add_i32 m0, s21, 0x3800
	v_mfma_f32_16x16x32_bf16 v[20:23], v[40:43], v[32:35], v[20:23]
	global_load_lds_dwordx4 v3, s[8:9]
	s_add_i32 m0, s21, 0x3c00
	v_mfma_f32_16x16x32_bf16 v[24:27], v[48:51], v[32:35], v[24:27]
	global_load_lds_dwordx4 v5, s[8:9]
	s_add_i32 m0, s21, 0x4000
	s_nop 0
	global_load_lds_dwordx4 v3, s[10:11]
	s_add_i32 m0, s21, 0x4400
	s_nop 0
	global_load_lds_dwordx4 v5, s[10:11]
	v_add_u32_e32 v3, 0x80, v3
	v_add_u32_e32 v5, 0x80, v5
	s_waitcnt vmcnt(12)
	ds_read_b128 v[28:31], v0 offset:0
	ds_read_b128 v[36:39], v0 offset:2048
	ds_read_b128 v[44:47], v0 offset:4096
	ds_read_b128 v[32:35], v0 offset:512
	ds_read_b128 v[40:43], v0 offset:2560
	ds_read_b128 v[48:51], v0 offset:4608
	s_waitcnt lgkmcnt(0)
	s_add_i32 m0, s21, 0x0
	v_mfma_f32_16x16x32_bf16 v[20:23], v[36:39], v[28:31], v[20:23]
	global_load_lds_dwordx4 v3, s[6:7]
	s_add_i32 m0, s21, 0x400
	v_mfma_f32_16x16x32_bf16 v[24:27], v[44:47], v[28:31], v[24:27]
	global_load_lds_dwordx4 v5, s[6:7]
	s_add_i32 m0, s21, 0x800
	v_mfma_f32_16x16x32_bf16 v[20:23], v[40:43], v[32:35], v[20:23]
	global_load_lds_dwordx4 v3, s[8:9]
	s_add_i32 m0, s21, 0xc00
	v_mfma_f32_16x16x32_bf16 v[24:27], v[48:51], v[32:35], v[24:27]
	global_load_lds_dwordx4 v5, s[8:9]
	s_add_i32 m0, s21, 0x1000
	s_nop 0
	global_load_lds_dwordx4 v3, s[10:11]
	s_add_i32 m0, s21, 0x1400
	s_nop 0
	global_load_lds_dwordx4 v5, s[10:11]
	v_add_u32_e32 v3, 0x80, v3
	v_add_u32_e32 v5, 0x80, v5
	s_waitcnt vmcnt(12)
	ds_read_b128 v[28:31], v0 offset:6144
	ds_read_b128 v[36:39], v0 offset:8192
	ds_read_b128 v[44:47], v0 offset:10240
	ds_read_b128 v[32:35], v0 offset:6656
	ds_read_b128 v[40:43], v0 offset:8704
	ds_read_b128 v[48:51], v0 offset:10752
	s_waitcnt lgkmcnt(0)
	s_add_i32 m0, s21, 0x1800
	v_mfma_f32_16x16x32_bf16 v[20:23], v[36:39], v[28:31], v[20:23]
	global_load_lds_dwordx4 v3, s[6:7]
	s_add_i32 m0, s21, 0x1c00
	v_mfma_f32_16x16x32_bf16 v[24:27], v[44:47], v[28:31], v[24:27]
	global_load_lds_dwordx4 v5, s[6:7]
	s_add_i32 m0, s21, 0x2000
	v_mfma_f32_16x16x32_bf16 v[20:23], v[40:43], v[32:35], v[20:23]
	global_load_lds_dwordx4 v3, s[8:9]
	s_add_i32 m0, s21, 0x2400
	v_mfma_f32_16x16x32_bf16 v[24:27], v[48:51], v[32:35], v[24:27]
	global_load_lds_dwordx4 v5, s[8:9]
	s_add_i32 m0, s21, 0x2800
	s_nop 0
	global_load_lds_dwordx4 v3, s[10:11]
	s_add_i32 m0, s21, 0x2c00
	s_nop 0
	global_load_lds_dwordx4 v5, s[10:11]
	v_add_u32_e32 v3, 0x80, v3
	v_add_u32_e32 v5, 0x80, v5
	s_waitcnt vmcnt(12)
	ds_read_b128 v[28:31], v0 offset:12288
	ds_read_b128 v[36:39], v0 offset:14336
	ds_read_b128 v[44:47], v0 offset:16384
	ds_read_b128 v[32:35], v0 offset:12800
	ds_read_b128 v[40:43], v0 offset:14848
	ds_read_b128 v[48:51], v0 offset:16896
	s_waitcnt lgkmcnt(0)
	s_add_i32 m0, s21, 0x3000
	v_mfma_f32_16x16x32_bf16 v[20:23], v[36:39], v[28:31], v[20:23]
	global_load_lds_dwordx4 v3, s[6:7]
	s_add_i32 m0, s21, 0x3400
	v_mfma_f32_16x16x32_bf16 v[24:27], v[44:47], v[28:31], v[24:27]
	global_load_lds_dwordx4 v5, s[6:7]
	s_add_i32 m0, s21, 0x3800
	v_mfma_f32_16x16x32_bf16 v[20:23], v[40:43], v[32:35], v[20:23]
	global_load_lds_dwordx4 v3, s[8:9]
	s_add_i32 m0, s21, 0x3c00
	v_mfma_f32_16x16x32_bf16 v[24:27], v[48:51], v[32:35], v[24:27]
	global_load_lds_dwordx4 v5, s[8:9]
	s_add_i32 m0, s21, 0x4000
	s_nop 0
	global_load_lds_dwordx4 v3, s[10:11]
	s_add_i32 m0, s21, 0x4400
	s_nop 0
	global_load_lds_dwordx4 v5, s[10:11]
	v_add_u32_e32 v3, 0x80, v3
	v_add_u32_e32 v5, 0x80, v5
	s_waitcnt vmcnt(12)
	ds_read_b128 v[28:31], v0 offset:0
	ds_read_b128 v[36:39], v0 offset:2048
	ds_read_b128 v[44:47], v0 offset:4096
	ds_read_b128 v[32:35], v0 offset:512
	ds_read_b128 v[40:43], v0 offset:2560
	ds_read_b128 v[48:51], v0 offset:4608
	s_waitcnt lgkmcnt(0)
	s_add_i32 m0, s21, 0x0
	v_mfma_f32_16x16x32_bf16 v[20:23], v[36:39], v[28:31], v[20:23]
	global_load_lds_dwordx4 v3, s[6:7]
	s_add_i32 m0, s21, 0x400
	v_mfma_f32_16x16x32_bf16 v[24:27], v[44:47], v[28:31], v[24:27]
	global_load_lds_dwordx4 v5, s[6:7]
	s_add_i32 m0, s21, 0x800
	v_mfma_f32_16x16x32_bf16 v[20:23], v[40:43], v[32:35], v[20:23]
	global_load_lds_dwordx4 v3, s[8:9]
	s_add_i32 m0, s21, 0xc00
	v_mfma_f32_16x16x32_bf16 v[24:27], v[48:51], v[32:35], v[24:27]
	global_load_lds_dwordx4 v5, s[8:9]
	s_add_i32 m0, s21, 0x1000
	s_nop 0
	global_load_lds_dwordx4 v3, s[10:11]
	s_add_i32 m0, s21, 0x1400
	s_nop 0
	global_load_lds_dwordx4 v5, s[10:11]
	v_add_u32_e32 v3, 0x80, v3
	v_add_u32_e32 v5, 0x80, v5
	s_waitcnt vmcnt(12)
	ds_read_b128 v[28:31], v0 offset:6144
	ds_read_b128 v[36:39], v0 offset:8192
	ds_read_b128 v[44:47], v0 offset:10240
	ds_read_b128 v[32:35], v0 offset:6656
	ds_read_b128 v[40:43], v0 offset:8704
	ds_read_b128 v[48:51], v0 offset:10752
	s_waitcnt lgkmcnt(0)
	s_add_i32 m0, s21, 0x1800
	v_mfma_f32_16x16x32_bf16 v[20:23], v[36:39], v[28:31], v[20:23]
	global_load_lds_dwordx4 v3, s[6:7]
	s_add_i32 m0, s21, 0x1c00
	v_mfma_f32_16x16x32_bf16 v[24:27], v[44:47], v[28:31], v[24:27]
	global_load_lds_dwordx4 v5, s[6:7]
	s_add_i32 m0, s21, 0x2000
	v_mfma_f32_16x16x32_bf16 v[20:23], v[40:43], v[32:35], v[20:23]
	global_load_lds_dwordx4 v3, s[8:9]
	s_add_i32 m0, s21, 0x2400
	v_mfma_f32_16x16x32_bf16 v[24:27], v[48:51], v[32:35], v[24:27]
	global_load_lds_dwordx4 v5, s[8:9]
	s_add_i32 m0, s21, 0x2800
	s_nop 0
	global_load_lds_dwordx4 v3, s[10:11]
	s_add_i32 m0, s21, 0x2c00
	s_nop 0
	global_load_lds_dwordx4 v5, s[10:11]
	v_add_u32_e32 v3, 0x80, v3
	v_add_u32_e32 v5, 0x80, v5
	s_waitcnt vmcnt(12)
	ds_read_b128 v[28:31], v0 offset:12288
	ds_read_b128 v[36:39], v0 offset:14336
	ds_read_b128 v[44:47], v0 offset:16384
	ds_read_b128 v[32:35], v0 offset:12800
	ds_read_b128 v[40:43], v0 offset:14848
	ds_read_b128 v[48:51], v0 offset:16896
	s_waitcnt lgkmcnt(0)
	s_add_i32 m0, s21, 0x3000
	v_mfma_f32_16x16x32_bf16 v[20:23], v[36:39], v[28:31], v[20:23]
	global_load_lds_dwordx4 v3, s[6:7]
	s_add_i32 m0, s21, 0x3400
	v_mfma_f32_16x16x32_bf16 v[24:27], v[44:47], v[28:31], v[24:27]
	global_load_lds_dwordx4 v5, s[6:7]
	s_add_i32 m0, s21, 0x3800
	v_mfma_f32_16x16x32_bf16 v[20:23], v[40:43], v[32:35], v[20:23]
	global_load_lds_dwordx4 v3, s[8:9]
	s_add_i32 m0, s21, 0x3c00
	v_mfma_f32_16x16x32_bf16 v[24:27], v[48:51], v[32:35], v[24:27]
	global_load_lds_dwordx4 v5, s[8:9]
	s_add_i32 m0, s21, 0x4000
	s_nop 0
	global_load_lds_dwordx4 v3, s[10:11]
	s_add_i32 m0, s21, 0x4400
	s_nop 0
	global_load_lds_dwordx4 v5, s[10:11]
	v_add_u32_e32 v3, 0x80, v3
	v_add_u32_e32 v5, 0x80, v5
	s_waitcnt vmcnt(12)
	ds_read_b128 v[28:31], v0 offset:0
	ds_read_b128 v[36:39], v0 offset:2048
	ds_read_b128 v[44:47], v0 offset:4096
	ds_read_b128 v[32:35], v0 offset:512
	ds_read_b128 v[40:43], v0 offset:2560
	ds_read_b128 v[48:51], v0 offset:4608
	s_waitcnt lgkmcnt(0)
	s_add_i32 m0, s21, 0x0
	v_mfma_f32_16x16x32_bf16 v[20:23], v[36:39], v[28:31], v[20:23]
	global_load_lds_dwordx4 v3, s[6:7]
	s_add_i32 m0, s21, 0x400
	v_mfma_f32_16x16x32_bf16 v[24:27], v[44:47], v[28:31], v[24:27]
	global_load_lds_dwordx4 v5, s[6:7]
	s_add_i32 m0, s21, 0x800
	v_mfma_f32_16x16x32_bf16 v[20:23], v[40:43], v[32:35], v[20:23]
	global_load_lds_dwordx4 v3, s[8:9]
	s_add_i32 m0, s21, 0xc00
	v_mfma_f32_16x16x32_bf16 v[24:27], v[48:51], v[32:35], v[24:27]
	global_load_lds_dwordx4 v5, s[8:9]
	s_add_i32 m0, s21, 0x1000
	s_nop 0
	global_load_lds_dwordx4 v3, s[10:11]
	s_add_i32 m0, s21, 0x1400
	s_nop 0
	global_load_lds_dwordx4 v5, s[10:11]
	v_add_u32_e32 v3, 0x80, v3
	v_add_u32_e32 v5, 0x80, v5
	s_waitcnt vmcnt(12)
	ds_read_b128 v[28:31], v0 offset:6144
	ds_read_b128 v[36:39], v0 offset:8192
	ds_read_b128 v[44:47], v0 offset:10240
	ds_read_b128 v[32:35], v0 offset:6656
	ds_read_b128 v[40:43], v0 offset:8704
	ds_read_b128 v[48:51], v0 offset:10752
	s_waitcnt lgkmcnt(0)
	v_mfma_f32_16x16x32_bf16 v[20:23], v[36:39], v[28:31], v[20:23]
	v_mfma_f32_16x16x32_bf16 v[24:27], v[44:47], v[28:31], v[24:27]
	v_mfma_f32_16x16x32_bf16 v[20:23], v[40:43], v[32:35], v[20:23]
	v_mfma_f32_16x16x32_bf16 v[24:27], v[48:51], v[32:35], v[24:27]
	s_waitcnt vmcnt(6)
	ds_read_b128 v[28:31], v0 offset:12288
	ds_read_b128 v[36:39], v0 offset:14336
	ds_read_b128 v[44:47], v0 offset:16384
	ds_read_b128 v[32:35], v0 offset:12800
	ds_read_b128 v[40:43], v0 offset:14848
	ds_read_b128 v[48:51], v0 offset:16896
	s_waitcnt lgkmcnt(0)
	v_mfma_f32_16x16x32_bf16 v[20:23], v[36:39], v[28:31], v[20:23]
	v_mfma_f32_16x16x32_bf16 v[24:27], v[44:47], v[28:31], v[24:27]
	v_mfma_f32_16x16x32_bf16 v[20:23], v[40:43], v[32:35], v[20:23]
	v_mfma_f32_16x16x32_bf16 v[24:27], v[48:51], v[32:35], v[24:27]
	s_waitcnt vmcnt(0)
	ds_read_b128 v[28:31], v0 offset:0
	ds_read_b128 v[36:39], v0 offset:2048
	ds_read_b128 v[44:47], v0 offset:4096
	ds_read_b128 v[32:35], v0 offset:512
	ds_read_b128 v[40:43], v0 offset:2560
	ds_read_b128 v[48:51], v0 offset:4608
	s_waitcnt lgkmcnt(0)
	v_mfma_f32_16x16x32_bf16 v[20:23], v[36:39], v[28:31], v[20:23]
	v_mfma_f32_16x16x32_bf16 v[24:27], v[44:47], v[28:31], v[24:27]
	v_mfma_f32_16x16x32_bf16 v[20:23], v[40:43], v[32:35], v[20:23]
	v_mfma_f32_16x16x32_bf16 v[24:27], v[48:51], v[32:35], v[24:27]
	v_mul_u32_u24_e32 v194, 0x1400, v12
	v_add3_u32 v194, v194, s13, v4
	v_lshl_add_u64 v[16:17], s[0:1], 0, v[194:195]
	v_ffbh_u32_e32 v13, v15
	v_min_u32_e32 v13, 32, v13
	v_lshlrev_b64 v[18:19], v13, v[14:15]
	v_min_u32_e32 v18, 1, v18
	v_or_b32_e32 v18, v19, v18
	v_cvt_f32_u32_e32 v18, v18
	v_sub_u32_e32 v13, 32, v13
	v_ldexp_f32 v13, v18, v13
	v_fmamk_f32 v13, v13, 0x2e800000, v236
	v_mul_f32_e32 v18, 0x4b800000, v13
	v_cmp_gt_f32_e32 vcc, s20, v13
	s_nop 1
	v_cndmask_b32_e32 v13, v13, v18, vcc
	v_rsq_f32_e32 v13, v13
	s_nop 0
	v_mul_f32_e32 v18, 0x45800000, v13
	v_cndmask_b32_e32 v18, v13, v18, vcc
	v_pk_mul_f32 v[20:21], v[20:21], v[18:19] op_sel_hi:[1,0]
	v_pk_mul_f32 v[22:23], v[22:23], v[18:19] op_sel_hi:[1,0]
	v_pk_mul_f32 v[24:25], v[24:25], v[18:19] op_sel_hi:[1,0]
	v_pk_mul_f32 v[26:27], v[26:27], v[18:19] op_sel_hi:[1,0]
	v_cvt_pk_bf16_f32 v20, v20, v21
	v_cvt_pk_bf16_f32 v21, v22, v23
	v_cvt_pk_bf16_f32 v24, v24, v25
	v_cvt_pk_bf16_f32 v25, v26, v27
	global_store_dwordx2 v[16:17], v[20:21], off
	global_store_dwordx2 v[16:17], v[24:25], off offset:32
	s_add_i32 s2, s2, 8
	s_cmp_lt_i32 s2, s3
	s_cbranch_scc1 .Lthinz_task
.LBB0_148:
	s_barrier
	s_add_i32 s0, s56, 1
	v_writelane_b32 v255, s0, 37
	s_cmp_lg_u32 s56, 3
	s_nop 0
	v_writelane_b32 v255, s1, 38
	s_cselect_b64 s[0:1], -1, 0
	v_writelane_b32 v255, s0, 39
	s_cmp_eq_u32 s56, 3
	s_nop 0
	v_writelane_b32 v255, s1, 40
	s_cbranch_scc1 .LBB0_256
	v_readlane_b32 s0, v255, 2
	v_readlane_b32 s1, v255, 3
	v_mov_b32_e32 v9, v195
	s_mov_b64 s[8:9], s[78:79]
	v_cndmask_b32_e64 v0, 0, 1, s[0:1]
	s_mov_b32 s0, 0x17d0000
	v_mul_lo_u32 v8, v0, s0
	s_mov_b32 s0, s89
	v_mbcnt_lo_u32_b32 v21, -1, 0
	v_mbcnt_hi_u32_b32 v21, -1, v21
	s_nop 0
	v_lshl_add_u32 v19, s0, 6, v21
	v_readlane_b32 s0, v255, 35
	v_readlane_b32 s1, v255, 36
	s_and_b64 vcc, exec, s[0:1]
	s_mov_b64 s[0:1], -1
	s_cbranch_vccnz .LBB0_202
	v_readlane_b32 s0, v255, 28
	s_xor_b32 s0, s0, 1
	s_mul_i32 s0, s0, 0x17d0000
	s_add_u32 s0, s8, s0
	s_addc_u32 s1, s9, 0
	s_add_u32 s10, s0, 0x78f0000
	s_mov_b32 s41, s81
	s_mov_b32 s40, s82
	s_addc_u32 s11, s1, 0
	s_cmpk_gt_i32 s40, 0x5d7
	s_cbranch_scc1 .LBB0_178
	s_add_u32 s56, s10, 0x500000
	s_addc_u32 s57, s11, 0
	s_add_u32 s58, s10, 0x700000
	s_addc_u32 s59, s11, 0
	s_cmpk_gt_i32 s40, 0x25f
	s_mov_b64 s[12:13], -1
	s_cbranch_scc0 .LBB0_157
	s_cmpk_gt_u32 s40, 0x35f
	s_mov_b64 s[6:7], -1
	s_cbranch_scc0 .LBB0_154
	s_lshl_b32 s0, s40, 2
	s_and_b32 s1, s0, 0x3fc0
	s_add_i32 s42, s1, 0xfffff280
	s_lshl_b32 s1, s42, 1
	s_and_b32 s1, s1, 0x1f00
	s_and_b32 s0, s0, 64
	s_or_b32 s7, s1, s0
	v_readlane_b32 s0, v255, 37
	v_readlane_b32 s12, v252, 50
	s_and_b32 s6, s40, 15
	s_mov_b32 s4, s0
	s_mul_i32 s0, s0, 0x1600000
	v_readlane_b32 s24, v252, 62
	v_readlane_b32 s1, v255, 38
	v_readlane_b32 s25, v252, 63
	s_add_u32 s0, s24, s0
	s_addc_u32 s1, s25, 0
	s_mul_i32 s2, s6, 0x160000
	s_add_u32 s2, s0, s2
	s_addc_u32 s3, s1, 0
	s_lshl_b64 s[0:1], s[42:43], 2
	s_add_u32 s2, s2, s0
	s_addc_u32 s3, s3, s1
	s_lshl_b32 s42, s4, 10
	v_readlane_b32 s22, v252, 60
	s_lshl_b64 s[0:1], s[42:43], 2
	v_readlane_b32 s23, v252, 61
	s_add_u32 s0, s22, s0
	s_addc_u32 s1, s23, s1
	s_lshl_b32 s4, s6, 8
	s_add_u32 s4, s0, s4
	s_addc_u32 s5, s1, 0
	s_lshl_b32 s0, s7, 11
	s_add_u32 s0, s58, s0
	s_addc_u32 s1, s59, 0
	s_lshl_b32 s6, s6, 7
	s_add_u32 s0, s0, s6
	v_readlane_b32 s13, v252, 51
	v_readlane_b32 s14, v252, 52
	v_readlane_b32 s15, v252, 53
	v_readlane_b32 s16, v252, 54
	v_readlane_b32 s17, v252, 55
	v_readlane_b32 s18, v252, 56
	v_readlane_b32 s19, v252, 57
	v_readlane_b32 s20, v252, 58
	v_readlane_b32 s21, v252, 59
	v_readlane_b32 s26, v253, 0
	v_readlane_b32 s27, v253, 1
	s_addc_u32 s1, s1, 0
	s_mov_b64 s[6:7], 0

.LBB0_873:
	s_andn2_b64 vcc, exec, s[0:1]
	s_cbranch_vccnz .LBB0_878
	v_readlane_b32 s0, v253, 7
	v_readlane_b32 s1, v253, 8
	s_andn2_b64 vcc, exec, s[0:1]
	s_cbranch_vccnz .LBB0_878
	v_readlane_b32 s3, v253, 11
	s_mul_i32 s2, s3, 11
	s_add_i32 s3, s2, 11
	s_add_i32 s2, s2, s89
	s_cmp_ge_i32 s2, s3
	s_cbranch_scc1 .LBB0_878
	v_and_b32_e32 v175, 63, v10
	v_and_b32_e32 v174, 15, v11
	v_lshrrev_b32_e32 v4, 2, v175
	v_and_b32_e32 v4, 12, v4
	v_lshlrev_b32_e32 v4, 1, v4
	v_bfe_u32 v6, v175, 2, 3
	v_and_b32_e32 v7, 3, v175
	v_lshrrev_b32_e32 v8, 5, v175
	v_lshlrev_b32_e32 v8, 6, v8
	v_lshrrev_b32_e32 v9, 2, v6
	v_sub_u32_e32 v10, 0, v9
	v_and_b32_e32 v10, 3, v10
	v_xor_b32_e32 v10, v10, v7
	v_lshl_or_b32 v1, v10, 4, v8
	v_lshl_or_b32 v1, v6, 11, v1
	v_sub_u32_e32 v10, 2, v9
	v_and_b32_e32 v10, 3, v10
	v_xor_b32_e32 v10, v10, v7
	v_lshl_or_b32 v2, v10, 4, v8
	v_add_u32_e32 v6, 8, v6
	v_lshl_or_b32 v2, v6, 11, v2
	v_lshrrev_b32_e32 v6, 4, v175
	v_lshrrev_b32_e32 v7, 2, v174
	v_sub_u32_e32 v7, 0, v7
	v_and_b32_e32 v7, 3, v7
	v_xor_b32_e32 v6, v6, v7
	v_lshlrev_b32_e32 v6, 4, v6
	v_and_b32_e32 v7, 7, v174
	v_lshl_or_b32 v6, v7, 6, v6
	v_lshrrev_b32_e32 v7, 3, v174
	v_lshl_or_b32 v6, v7, 10, v6
	s_mul_i32 s21, s89, 0x4800
	v_add_u32_e32 v0, s21, v6
	s_mov_b64 s[22:23], s[4:5]
	s_add_u32 s16, s16, 0x2000000
	s_addc_u32 s17, s17, 0
	s_waitcnt vmcnt(0) lgkmcnt(0)
.Lthina_task:
	s_and_b32 s0, s2, 7
	s_lshl_b32 s0, s0, 4
	s_lshr_b32 s1, s2, 3
	s_lshr_b32 s4, s1, 3
	s_lshl_b32 s4, s4, 8
	s_and_b32 s5, s1, 7
	s_lshl_b32 s5, s5, 4
	s_or_b32 s4, s4, s5
	s_lshl_b32 s5, s1, 5
	s_lshl_b32 s4, s4, 11
	s_lshl_b32 s6, s0, 11
	s_add_u32 s8, s22, s4
	s_addc_u32 s9, s23, 0
	s_add_u32 s10, s8, 0x40000
	s_addc_u32 s11, s9, 0
	s_add_u32 s6, s16, s6
	s_addc_u32 s7, s17, 0
	v_or_b32_e32 v13, s0, v174
	v_or_b32_e32 v12, 0x4000, v13
	v_lshlrev_b32_e32 v194, 3, v12
	v_lshl_add_u64 v[14:15], s[14:15], 0, v[194:195]
	global_load_dwordx2 v[14:15], v[14:15], off
	v_mov_b32_e32 v3, v1
	v_mov_b32_e32 v5, v2
	s_add_i32 m0, s21, 0x0
	s_nop 0
	global_load_lds_dwordx4 v3, s[6:7]
	s_add_i32 m0, s21, 0x400
	s_nop 0
	global_load_lds_dwordx4 v5, s[6:7]
	s_add_i32 m0, s21, 0x800
	s_nop 0
	global_load_lds_dwordx4 v3, s[8:9]
	s_add_i32 m0, s21, 0xc00
	s_nop 0
	global_load_lds_dwordx4 v5, s[8:9]
	s_add_i32 m0, s21, 0x1000
	s_nop 0
	global_load_lds_dwordx4 v3, s[10:11]
	s_add_i32 m0, s21, 0x1400
	s_nop 0
	global_load_lds_dwordx4 v5, s[10:11]
	v_add_u32_e32 v3, 0x80, v3
	v_add_u32_e32 v5, 0x80, v5
	s_add_i32 m0, s21, 0x1800
	s_nop 0
	global_load_lds_dwordx4 v3, s[6:7]
	s_add_i32 m0, s21, 0x1c00
	s_nop 0
	global_load_lds_dwordx4 v5, s[6:7]
	s_add_i32 m0, s21, 0x2000
	s_nop 0
	global_load_lds_dwordx4 v3, s[8:9]
	s_add_i32 m0, s21, 0x2400
	s_nop 0
	global_load_lds_dwordx4 v5, s[8:9]
	s_add_i32 m0, s21, 0x2800
	s_nop 0
	global_load_lds_dwordx4 v3, s[10:11]
	s_add_i32 m0, s21, 0x2c00
	s_nop 0
	global_load_lds_dwordx4 v5, s[10:11]
	v_add_u32_e32 v3, 0x80, v3
	v_add_u32_e32 v5, 0x80, v5
	s_add_i32 m0, s21, 0x3000
	s_nop 0
	global_load_lds_dwordx4 v3, s[6:7]
	s_add_i32 m0, s21, 0x3400
	s_nop 0
	global_load_lds_dwordx4 v5, s[6:7]
	s_add_i32 m0, s21, 0x3800
	s_nop 0
	global_load_lds_dwordx4 v3, s[8:9]
	s_add_i32 m0, s21, 0x3c00
	s_nop 0
	global_load_lds_dwordx4 v5, s[8:9]
	s_add_i32 m0, s21, 0x4000
	s_nop 0
	global_load_lds_dwordx4 v3, s[10:11]
	s_add_i32 m0, s21, 0x4400
	s_nop 0
	global_load_lds_dwordx4 v5, s[10:11]
	v_add_u32_e32 v3, 0x80, v3
	v_add_u32_e32 v5, 0x80, v5
	s_waitcnt vmcnt(12)
	ds_read_b128 v[28:31], v0 offset:0
	ds_read_b128 v[36:39], v0 offset:2048
	ds_read_b128 v[44:47], v0 offset:4096
	ds_read_b128 v[32:35], v0 offset:512
	ds_read_b128 v[40:43], v0 offset:2560
	ds_read_b128 v[48:51], v0 offset:4608
	s_waitcnt lgkmcnt(0)
	s_add_i32 m0, s21, 0x0
	v_mfma_f32_16x16x32_bf16 v[20:23], v[36:39], v[28:31], 0
	global_load_lds_dwordx4 v3, s[6:7]
	s_add_i32 m0, s21, 0x400
	v_mfma_f32_16x16x32_bf16 v[24:27], v[44:47], v[28:31], 0
	global_load_lds_dwordx4 v5, s[6:7]
	s_add_i32 m0, s21, 0x800
	v_mfma_f32_16x16x32_bf16 v[20:23], v[40:43], v[32:35], v[20:23]
	global_load_lds_dwordx4 v3, s[8:9]
	s_add_i32 m0, s21, 0xc00
	v_mfma_f32_16x16x32_bf16 v[24:27], v[48:51], v[32:35], v[24:27]
	global_load_lds_dwordx4 v5, s[8:9]
	s_add_i32 m0, s21, 0x1000
	s_nop 0
	global_load_lds_dwordx4 v3, s[10:11]
	s_add_i32 m0, s21, 0x1400
	s_nop 0
	global_load_lds_dwordx4 v5, s[10:11]
	v_add_u32_e32 v3, 0x80, v3
	v_add_u32_e32 v5, 0x80, v5
	s_waitcnt vmcnt(12)
	ds_read_b128 v[28:31], v0 offset:6144
	ds_read_b128 v[36:39], v0 offset:8192
	ds_read_b128 v[44:47], v0 offset:10240
	ds_read_b128 v[32:35], v0 offset:6656
	ds_read_b128 v[40:43], v0 offset:8704
	ds_read_b128 v[48:51], v0 offset:10752
	s_waitcnt lgkmcnt(0)
	s_add_i32 m0, s21, 0x1800
	v_mfma_f32_16x16x32_bf16 v[20:23], v[36:39], v[28:31], v[20:23]
	global_load_lds_dwordx4 v3, s[6:7]
	s_add_i32 m0, s21, 0x1c00
	v_mfma_f32_16x16x32_bf16 v[24:27], v[44:47], v[28:31], v[24:27]
	global_load_lds_dwordx4 v5, s[6:7]
	s_add_i32 m0, s21, 0x2000
	v_mfma_f32_16x16x32_bf16 v[20:23], v[40:43], v[32:35], v[20:23]
	global_load_lds_dwordx4 v3, s[8:9]
	s_add_i32 m0, s21, 0x2400
	v_mfma_f32_16x16x32_bf16 v[24:27], v[48:51], v[32:35], v[24:27]
	global_load_lds_dwordx4 v5, s[8:9]
	s_add_i32 m0, s21, 0x2800
	s_nop 0
	global_load_lds_dwordx4 v3, s[10:11]
	s_add_i32 m0, s21, 0x2c00
	s_nop 0
	global_load_lds_dwordx4 v5, s[10:11]
	v_add_u32_e32 v3, 0x80, v3
	v_add_u32_e32 v5, 0x80, v5
	s_waitcnt vmcnt(12)
	ds_read_b128 v[28:31], v0 offset:12288
	ds_read_b128 v[36:39], v0 offset:14336
	ds_read_b128 v[44:47], v0 offset:16384
	ds_read_b128 v[32:35], v0 offset:12800
	ds_read_b128 v[40:43], v0 offset:14848
	ds_read_b128 v[48:51], v0 offset:16896
	s_waitcnt lgkmcnt(0)
	s_add_i32 m0, s21, 0x3000
	v_mfma_f32_16x16x32_bf16 v[20:23], v[36:39], v[28:31], v[20:23]
	global_load_lds_dwordx4 v3, s[6:7]
	s_add_i32 m0, s21, 0x3400
	v_mfma_f32_16x16x32_bf16 v[24:27], v[44:47], v[28:31], v[24:27]
	global_load_lds_dwordx4 v5, s[6:7]
	s_add_i32 m0, s21, 0x3800
	v_mfma_f32_16x16x32_bf16 v[20:23], v[40:43], v[32:35], v[20:23]
	global_load_lds_dwordx4 v3, s[8:9]
	s_add_i32 m0, s21, 0x3c00
	v_mfma_f32_16x16x32_bf16 v[24:27], v[48:51], v[32:35], v[24:27]
	global_load_lds_dwordx4 v5, s[8:9]
	s_add_i32 m0, s21, 0x4000
	s_nop 0
	global_load_lds_dwordx4 v3, s[10:11]
	s_add_i32 m0, s21, 0x4400
	s_nop 0
	global_load_lds_dwordx4 v5, s[10:11]
	v_add_u32_e32 v3, 0x80, v3
	v_add_u32_e32 v5, 0x80, v5
	s_waitcnt vmcnt(12)
	ds_read_b128 v[28:31], v0 offset:0
	ds_read_b128 v[36:39], v0 offset:2048
	ds_read_b128 v[44:47], v0 offset:4096
	ds_read_b128 v[32:35], v0 offset:512
	ds_read_b128 v[40:43], v0 offset:2560
	ds_read_b128 v[48:51], v0 offset:4608
	s_waitcnt lgkmcnt(0)
	s_add_i32 m0, s21, 0x0
	v_mfma_f32_16x16x32_bf16 v[20:23], v[36:39], v[28:31], v[20:23]
	global_load_lds_dwordx4 v3, s[6:7]
	s_add_i32 m0, s21, 0x400
	v_mfma_f32_16x16x32_bf16 v[24:27], v[44:47], v[28:31], v[24:27]
	global_load_lds_dwordx4 v5, s[6:7]
	s_add_i32 m0, s21, 0x800
	v_mfma_f32_16x16x32_bf16 v[20:23], v[40:43], v[32:35], v[20:23]
	global_load_lds_dwordx4 v3, s[8:9]
	s_add_i32 m0, s21, 0xc00
	v_mfma_f32_16x16x32_bf16 v[24:27], v[48:51], v[32:35], v[24:27]
	global_load_lds_dwordx4 v5, s[8:9]
	s_add_i32 m0, s21, 0x1000
	s_nop 0
	global_load_lds_dwordx4 v3, s[10:11]
	s_add_i32 m0, s21, 0x1400
	s_nop 0
	global_load_lds_dwordx4 v5, s[10:11]
	v_add_u32_e32 v3, 0x80, v3
	v_add_u32_e32 v5, 0x80, v5
	s_waitcnt vmcnt(12)
	ds_read_b128 v[28:31], v0 offset:6144
	ds_read_b128 v[36:39], v0 offset:8192
	ds_read_b128 v[44:47], v0 offset:10240
	ds_read_b128 v[32:35], v0 offset:6656
	ds_read_b128 v[40:43], v0 offset:8704
	ds_read_b128 v[48:51], v0 offset:10752
	s_waitcnt lgkmcnt(0)
	s_add_i32 m0, s21, 0x1800
	v_mfma_f32_16x16x32_bf16 v[20:23], v[36:39], v[28:31], v[20:23]
	global_load_lds_dwordx4 v3, s[6:7]
	s_add_i32 m0, s21, 0x1c00
	v_mfma_f32_16x16x32_bf16 v[24:27], v[44:47], v[28:31], v[24:27]
	global_load_lds_dwordx4 v5, s[6:7]
	s_add_i32 m0, s21, 0x2000
	v_mfma_f32_16x16x32_bf16 v[20:23], v[40:43], v[32:35], v[20:23]
	global_load_lds_dwordx4 v3, s[8:9]
	s_add_i32 m0, s21, 0x2400
	v_mfma_f32_16x16x32_bf16 v[24:27], v[48:51], v[32:35], v[24:27]
	global_load_lds_dwordx4 v5, s[8:9]
	s_add_i32 m0, s21, 0x2800
	s_nop 0
	global_load_lds_dwordx4 v3, s[10:11]
	s_add_i32 m0, s21, 0x2c00
	s_nop 0
	global_load_lds_dwordx4 v5, s[10:11]
	v_add_u32_e32 v3, 0x80, v3
	v_add_u32_e32 v5, 0x80, v5
	s_waitcnt vmcnt(12)
	ds_read_b128 v[28:31], v0 offset:12288
	ds_read_b128 v[36:39], v0 offset:14336
	ds_read_b128 v[44:47], v0 offset:16384
	ds_read_b128 v[32:35], v0 offset:12800
	ds_read_b128 v[40:43], v0 offset:14848
	ds_read_b128 v[48:51], v0 offset:16896
	s_waitcnt lgkmcnt(0)
	s_add_i32 m0, s21, 0x3000
	v_mfma_f32_16x16x32_bf16 v[20:23], v[36:39], v[28:31], v[20:23]
	global_load_lds_dwordx4 v3, s[6:7]
	s_add_i32 m0, s21, 0x3400
	v_mfma_f32_16x16x32_bf16 v[24:27], v[44:47], v[28:31], v[24:27]
	global_load_lds_dwordx4 v5, s[6:7]
	s_add_i32 m0, s21, 0x3800
	v_mfma_f32_16x16x32_bf16 v[20:23], v[40:43], v[32:35], v[20:23]
	global_load_lds_dwordx4 v3, s[8:9]
	s_add_i32 m0, s21, 0x3c00
	v_mfma_f32_16x16x32_bf16 v[24:27], v[48:51], v[32:35], v[24:27]
	global_load_lds_dwordx4 v5, s[8:9]
	s_add_i32 m0, s21, 0x4000
	s_nop 0
	global_load_lds_dwordx4 v3, s[10:11]
	s_add_i32 m0, s21, 0x4400
	s_nop 0
	global_load_lds_dwordx4 v5, s[10:11]
	v_add_u32_e32 v3, 0x80, v3
	v_add_u32_e32 v5, 0x80, v5
	s_waitcnt vmcnt(12)
	ds_read_b128 v[28:31], v0 offset:0
	ds_read_b128 v[36:39], v0 offset:2048
	ds_read_b128 v[44:47], v0 offset:4096
	ds_read_b128 v[32:35], v0 offset:512
	ds_read_b128 v[40:43], v0 offset:2560
	ds_read_b128 v[48:51], v0 offset:4608
	s_waitcnt lgkmcnt(0)
	s_add_i32 m0, s21, 0x0
	v_mfma_f32_16x16x32_bf16 v[20:23], v[36:39], v[28:31], v[20:23]
	global_load_lds_dwordx4 v3, s[6:7]
	s_add_i32 m0, s21, 0x400
	v_mfma_f32_16x16x32_bf16 v[24:27], v[44:47], v[28:31], v[24:27]
	global_load_lds_dwordx4 v5, s[6:7]
	s_add_i32 m0, s21, 0x800
	v_mfma_f32_16x16x32_bf16 v[20:23], v[40:43], v[32:35], v[20:23]
	global_load_lds_dwordx4 v3, s[8:9]
	s_add_i32 m0, s21, 0xc00
	v_mfma_f32_16x16x32_bf16 v[24:27], v[48:51], v[32:35], v[24:27]
	global_load_lds_dwordx4 v5, s[8:9]
	s_add_i32 m0, s21, 0x1000
	s_nop 0
	global_load_lds_dwordx4 v3, s[10:11]
	s_add_i32 m0, s21, 0x1400
	s_nop 0
	global_load_lds_dwordx4 v5, s[10:11]
	v_add_u32_e32 v3, 0x80, v3
	v_add_u32_e32 v5, 0x80, v5
	s_waitcnt vmcnt(12)
	ds_read_b128 v[28:31], v0 offset:6144
	ds_read_b128 v[36:39], v0 offset:8192
	ds_read_b128 v[44:47], v0 offset:10240
	ds_read_b128 v[32:35], v0 offset:6656
	ds_read_b128 v[40:43], v0 offset:8704
	ds_read_b128 v[48:51], v0 offset:10752
	s_waitcnt lgkmcnt(0)
	s_add_i32 m0, s21, 0x1800
	v_mfma_f32_16x16x32_bf16 v[20:23], v[36:39], v[28:31], v[20:23]
	global_load_lds_dwordx4 v3, s[6:7]
	s_add_i32 m0, s21, 0x1c00
	v_mfma_f32_16x16x32_bf16 v[24:27], v[44:47], v[28:31], v[24:27]
	global_load_lds_dwordx4 v5, s[6:7]
	s_add_i32 m0, s21, 0x2000
	v_mfma_f32_16x16x32_bf16 v[20:23], v[40:43], v[32:35], v[20:23]
	global_load_lds_dwordx4 v3, s[8:9]
	s_add_i32 m0, s21, 0x2400
	v_mfma_f32_16x16x32_bf16 v[24:27], v[48:51], v[32:35], v[24:27]
	global_load_lds_dwordx4 v5, s[8:9]
	s_add_i32 m0, s21, 0x2800
	s_nop 0
	global_load_lds_dwordx4 v3, s[10:11]
	s_add_i32 m0, s21, 0x2c00
	s_nop 0
	global_load_lds_dwordx4 v5, s[10:11]
	v_add_u32_e32 v3, 0x80, v3
	v_add_u32_e32 v5, 0x80, v5
	s_waitcnt vmcnt(12)
	ds_read_b128 v[28:31], v0 offset:12288
	ds_read_b128 v[36:39], v0 offset:14336
	ds_read_b128 v[44:47], v0 offset:16384
	ds_read_b128 v[32:35], v0 offset:12800
	ds_read_b128 v[40:43], v0 offset:14848
	ds_read_b128 v[48:51], v0 offset:16896
	s_waitcnt lgkmcnt(0)
	s_add_i32 m0, s21, 0x3000
	v_mfma_f32_16x16x32_bf16 v[20:23], v[36:39], v[28:31], v[20:23]
	global_load_lds_dwordx4 v3, s[6:7]
	s_add_i32 m0, s21, 0x3400
	v_mfma_f32_16x16x32_bf16 v[24:27], v[44:47], v[28:31], v[24:27]
	global_load_lds_dwordx4 v5, s[6:7]
	s_add_i32 m0, s21, 0x3800
	v_mfma_f32_16x16x32_bf16 v[20:23], v[40:43], v[32:35], v[20:23]
	global_load_lds_dwordx4 v3, s[8:9]
	s_add_i32 m0, s21, 0x3c00
	v_mfma_f32_16x16x32_bf16 v[24:27], v[48:51], v[32:35], v[24:27]
	global_load_lds_dwordx4 v5, s[8:9]
	s_add_i32 m0, s21, 0x4000
	s_nop 0
	global_load_lds_dwordx4 v3, s[10:11]
	s_add_i32 m0, s21, 0x4400
	s_nop 0
	global_load_lds_dwordx4 v5, s[10:11]
	v_add_u32_e32 v3, 0x80, v3
	v_add_u32_e32 v5, 0x80, v5
	s_waitcnt vmcnt(12)
	ds_read_b128 v[28:31], v0 offset:0
	ds_read_b128 v[36:39], v0 offset:2048
	ds_read_b128 v[44:47], v0 offset:4096
	ds_read_b128 v[32:35], v0 offset:512
	ds_read_b128 v[40:43], v0 offset:2560
	ds_read_b128 v[48:51], v0 offset:4608
	s_waitcnt lgkmcnt(0)
	s_add_i32 m0, s21, 0x0
	v_mfma_f32_16x16x32_bf16 v[20:23], v[36:39], v[28:31], v[20:23]
	global_load_lds_dwordx4 v3, s[6:7]
	s_add_i32 m0, s21, 0x400
	v_mfma_f32_16x16x32_bf16 v[24:27], v[44:47], v[28:31], v[24:27]
	global_load_lds_dwordx4 v5, s[6:7]
	s_add_i32 m0, s21, 0x800
	v_mfma_f32_16x16x32_bf16 v[20:23], v[40:43], v[32:35], v[20:23]
	global_load_lds_dwordx4 v3, s[8:9]
	s_add_i32 m0, s21, 0xc00
	v_mfma_f32_16x16x32_bf16 v[24:27], v[48:51], v[32:35], v[24:27]
	global_load_lds_dwordx4 v5, s[8:9]
	s_add_i32 m0, s21, 0x1000
	s_nop 0
	global_load_lds_dwordx4 v3, s[10:11]
	s_add_i32 m0, s21, 0x1400
	s_nop 0
	global_load_lds_dwordx4 v5, s[10:11]
	v_add_u32_e32 v3, 0x80, v3
	v_add_u32_e32 v5, 0x80, v5
	s_waitcnt vmcnt(12)
	ds_read_b128 v[28:31], v0 offset:6144
	ds_read_b128 v[36:39], v0 offset:8192
	ds_read_b128 v[44:47], v0 offset:10240
	ds_read_b128 v[32:35], v0 offset:6656
	ds_read_b128 v[40:43], v0 offset:8704
	ds_read_b128 v[48:51], v0 offset:10752
	s_waitcnt lgkmcnt(0)
	s_add_i32 m0, s21, 0x1800
	v_mfma_f32_16x16x32_bf16 v[20:23], v[36:39], v[28:31], v[20:23]
	global_load_lds_dwordx4 v3, s[6:7]
	s_add_i32 m0, s21, 0x1c00
	v_mfma_f32_16x16x32_bf16 v[24:27], v[44:47], v[28:31], v[24:27]
	global_load_lds_dwordx4 v5, s[6:7]
	s_add_i32 m0, s21, 0x2000
	v_mfma_f32_16x16x32_bf16 v[20:23], v[40:43], v[32:35], v[20:23]
	global_load_lds_dwordx4 v3, s[8:9]
	s_add_i32 m0, s21, 0x2400
	v_mfma_f32_16x16x32_bf16 v[24:27], v[48:51], v[32:35], v[24:27]
	global_load_lds_dwordx4 v5, s[8:9]
	s_add_i32 m0, s21, 0x2800
	s_nop 0
	global_load_lds_dwordx4 v3, s[10:11]
	s_add_i32 m0, s21, 0x2c00
	s_nop 0
	global_load_lds_dwordx4 v5, s[10:11]
	v_add_u32_e32 v3, 0x80, v3
	v_add_u32_e32 v5, 0x80, v5
	s_waitcnt vmcnt(12)
	ds_read_b128 v[28:31], v0 offset:12288
	ds_read_b128 v[36:39], v0 offset:14336
	ds_read_b128 v[44:47], v0 offset:16384
	ds_read_b128 v[32:35], v0 offset:12800
	ds_read_b128 v[40:43], v0 offset:14848
	ds_read_b128 v[48:51], v0 offset:16896
	s_waitcnt lgkmcnt(0)
	s_add_i32 m0, s21, 0x3000
	v_mfma_f32_16x16x32_bf16 v[20:23], v[36:39], v[28:31], v[20:23]
	global_load_lds_dwordx4 v3, s[6:7]
	s_add_i32 m0, s21, 0x3400
	v_mfma_f32_16x16x32_bf16 v[24:27], v[44:47], v[28:31], v[24:27]
	global_load_lds_dwordx4 v5, s[6:7]
	s_add_i32 m0, s21, 0x3800
	v_mfma_f32_16x16x32_bf16 v[20:23], v[40:43], v[32:35], v[20:23]
	global_load_lds_dwordx4 v3, s[8:9]
	s_add_i32 m0, s21, 0x3c00
	v_mfma_f32_16x16x32_bf16 v[24:27], v[48:51], v[32:35], v[24:27]
	global_load_lds_dwordx4 v5, s[8:9]
	s_add_i32 m0, s21, 0x4000
	s_nop 0
	global_load_lds_dwordx4 v3, s[10:11]
	s_add_i32 m0, s21, 0x4400
	s_nop 0
	global_load_lds_dwordx4 v5, s[10:11]
	v_add_u32_e32 v3, 0x80, v3
	v_add_u32_e32 v5, 0x80, v5
	s_waitcnt vmcnt(12)
	ds_read_b128 v[28:31], v0 offset:0
	ds_read_b128 v[36:39], v0 offset:2048
	ds_read_b128 v[44:47], v0 offset:4096
	ds_read_b128 v[32:35], v0 offset:512
	ds_read_b128 v[40:43], v0 offset:2560
	ds_read_b128 v[48:51], v0 offset:4608
	s_waitcnt lgkmcnt(0)
	s_add_i32 m0, s21, 0x0
	v_mfma_f32_16x16x32_bf16 v[20:23], v[36:39], v[28:31], v[20:23]
	global_load_lds_dwordx4 v3, s[6:7]
	s_add_i32 m0, s21, 0x400
	v_mfma_f32_16x16x32_bf16 v[24:27], v[44:47], v[28:31], v[24:27]
	global_load_lds_dwordx4 v5, s[6:7]
	s_add_i32 m0, s21, 0x800
	v_mfma_f32_16x16x32_bf16 v[20:23], v[40:43], v[32:35], v[20:23]
	global_load_lds_dwordx4 v3, s[8:9]
	s_add_i32 m0, s21, 0xc00
	v_mfma_f32_16x16x32_bf16 v[24:27], v[48:51], v[32:35], v[24:27]
	global_load_lds_dwordx4 v5, s[8:9]
	s_add_i32 m0, s21, 0x1000
	s_nop 0
	global_load_lds_dwordx4 v3, s[10:11]
	s_add_i32 m0, s21, 0x1400
	s_nop 0
	global_load_lds_dwordx4 v5, s[10:11]
	v_add_u32_e32 v3, 0x80, v3
	v_add_u32_e32 v5, 0x80, v5
	s_waitcnt vmcnt(12)
	ds_read_b128 v[28:31], v0 offset:6144
	ds_read_b128 v[36:39], v0 offset:8192
	ds_read_b128 v[44:47], v0 offset:10240
	ds_read_b128 v[32:35], v0 offset:6656
	ds_read_b128 v[40:43], v0 offset:8704
	ds_read_b128 v[48:51], v0 offset:10752
	s_waitcnt lgkmcnt(0)
	v_mfma_f32_16x16x32_bf16 v[20:23], v[36:39], v[28:31], v[20:23]
	v_mfma_f32_16x16x32_bf16 v[24:27], v[44:47], v[28:31], v[24:27]
	v_mfma_f32_16x16x32_bf16 v[20:23], v[40:43], v[32:35], v[20:23]
	v_mfma_f32_16x16x32_bf16 v[24:27], v[48:51], v[32:35], v[24:27]
	s_waitcnt vmcnt(6)
	ds_read_b128 v[28:31], v0 offset:12288
	ds_read_b128 v[36:39], v0 offset:14336
	ds_read_b128 v[44:47], v0 offset:16384
	ds_read_b128 v[32:35], v0 offset:12800
	ds_read_b128 v[40:43], v0 offset:14848
	ds_read_b128 v[48:51], v0 offset:16896
	s_waitcnt lgkmcnt(0)
	v_mfma_f32_16x16x32_bf16 v[20:23], v[36:39], v[28:31], v[20:23]
	v_mfma_f32_16x16x32_bf16 v[24:27], v[44:47], v[28:31], v[24:27]
	v_mfma_f32_16x16x32_bf16 v[20:23], v[40:43], v[32:35], v[20:23]
	v_mfma_f32_16x16x32_bf16 v[24:27], v[48:51], v[32:35], v[24:27]
	s_waitcnt vmcnt(0)
	ds_read_b128 v[28:31], v0 offset:0
	ds_read_b128 v[36:39], v0 offset:2048
	ds_read_b128 v[44:47], v0 offset:4096
	ds_read_b128 v[32:35], v0 offset:512
	ds_read_b128 v[40:43], v0 offset:2560
	ds_read_b128 v[48:51], v0 offset:4608
	s_waitcnt lgkmcnt(0)
	v_mfma_f32_16x16x32_bf16 v[20:23], v[36:39], v[28:31], v[20:23]
	v_mfma_f32_16x16x32_bf16 v[24:27], v[44:47], v[28:31], v[24:27]
	v_mfma_f32_16x16x32_bf16 v[20:23], v[40:43], v[32:35], v[20:23]
	v_mfma_f32_16x16x32_bf16 v[24:27], v[48:51], v[32:35], v[24:27]
	v_mul_u32_u24_e32 v194, 0x1600, v12
	v_add3_u32 v194, v194, s5, v4
	v_lshl_add_u64 v[16:17], s[12:13], 0, v[194:195]
	v_ffbh_u32_e32 v13, v15
	v_min_u32_e32 v13, 32, v13
	v_lshlrev_b64 v[18:19], v13, v[14:15]
	v_min_u32_e32 v18, 1, v18
	v_or_b32_e32 v18, v19, v18
	v_cvt_f32_u32_e32 v18, v18
	v_sub_u32_e32 v13, 32, v13
	v_ldexp_f32 v13, v18, v13
	v_fmamk_f32 v13, v13, 0x2e800000, v236
	v_mul_f32_e32 v18, 0x4b800000, v13
	v_cmp_gt_f32_e32 vcc, s20, v13
	s_nop 1
	v_cndmask_b32_e32 v13, v13, v18, vcc
	v_rsq_f32_e32 v13, v13
	s_nop 0
	v_mul_f32_e32 v18, 0x45800000, v13
	v_cndmask_b32_e32 v18, v13, v18, vcc
	v_pk_mul_f32 v[20:21], v[20:21], v[18:19] op_sel_hi:[1,0]
	v_pk_mul_f32 v[22:23], v[22:23], v[18:19] op_sel_hi:[1,0]
	v_pk_mul_f32 v[24:25], v[24:25], v[18:19] op_sel_hi:[1,0]
	v_pk_mul_f32 v[26:27], v[26:27], v[18:19] op_sel_hi:[1,0]
	v_mul_f32_e32 v28, 0xbfb8aa3b, v20
	v_mul_f32_e32 v29, 0xbfb8aa3b, v21
	v_mul_f32_e32 v30, 0xbfb8aa3b, v22
	v_mul_f32_e32 v31, 0xbfb8aa3b, v23
	v_exp_f32_e32 v28, v28
	v_exp_f32_e32 v29, v29
	v_exp_f32_e32 v30, v30
	v_exp_f32_e32 v31, v31
	v_pk_add_f32 v[28:29], v[28:29], 1.0 op_sel_hi:[1,0]
	v_pk_add_f32 v[30:31], v[30:31], 1.0 op_sel_hi:[1,0]
	v_rcp_f32_e32 v28, v28
	v_rcp_f32_e32 v29, v29
	v_rcp_f32_e32 v30, v30
	v_rcp_f32_e32 v31, v31
	v_pk_mul_f32 v[20:21], v[20:21], v[28:29]
	v_pk_mul_f32 v[22:23], v[22:23], v[30:31]
	v_pk_mul_f32 v[20:21], v[20:21], v[24:25]
	v_pk_mul_f32 v[22:23], v[22:23], v[26:27]
	v_cvt_pk_bf16_f32 v20, v20, v21
	v_cvt_pk_bf16_f32 v21, v22, v23
	global_store_dwordx2 v[16:17], v[20:21], off
	s_add_i32 s2, s2, 8
	s_cmp_lt_i32 s2, s3
	s_cbranch_scc1 .Lthina_task
.LBB0_878:
	s_barrier
	v_readlane_b32 s0, v255, 39
	v_readlane_b32 s1, v255, 40
	s_andn2_b64 vcc, exec, s[0:1]
	s_cbranch_vccnz .LBB0_984
	s_mov_b32 s0, s89
	v_readlane_b32 s2, v255, 35
	v_readlane_b32 s3, v255, 36
	v_mbcnt_lo_u32_b32 v17, -1, 0
	v_mbcnt_hi_u32_b32 v17, -1, v17
	s_and_b64 vcc, exec, s[2:3]
	v_lshl_add_u32 v19, s0, 6, v17
	s_mov_b64 s[0:1], s[78:79]
	s_mov_b64 s[2:3], -1
	s_cbranch_vccnz .LBB0_931
	s_mov_b32 s66, s82
	s_mov_b32 s67, s81
	s_mov_b32 s64, s97
	s_cmpk_gt_i32 s66, 0x5d7
	s_cbranch_scc1 .LBB0_930
	v_readlane_b32 s2, v255, 28
	s_xor_b32 s2, s2, 1
	s_mul_i32 s2, s2, 0x17d0000
	s_add_u32 s2, s0, s2
	s_addc_u32 s3, s1, 0
	s_add_u32 s68, s2, 0x78f0000
	s_addc_u32 s69, s3, 0
	s_add_i32 s59, s66, 0x5d8
	s_add_u32 s70, s2, 0x7df0000
	s_addc_u32 s71, s3, 0
	s_add_u32 s72, s2, 0x7ff0000
	s_addc_u32 s73, s3, 0
	s_add_u32 s76, s2, 0x8af0000
	s_addc_u32 s77, s3, 0
	s_add_u32 s83, s2, 0x9070000
	s_addc_u32 s97, s3, 0
	s_cmpk_gt_i32 s66, 0xfc87
	s_mov_b64 s[10:11], -1
	s_cbranch_scc0 .LBB0_898
	s_cmpk_gt_u32 s59, 0x35f
	s_cbranch_scc0 .LBB0_895
	s_cmpk_gt_u32 s59, 0x8df
	s_mov_b64 s[8:9], -1
	s_cbranch_scc0 .LBB0_888
	v_readlane_b32 s2, v255, 37
	v_readlane_b32 s3, v255, 38
	s_mov_b32 s3, s43
	v_writelane_b32 v255, s2, 37
	s_cmpk_gt_u32 s59, 0xb9f
	s_mov_b64 s[6:7], -1
	v_writelane_b32 v255, s3, 38
	s_cbranch_scc0 .LBB0_886
	s_add_i32 s2, s66, 0xfffffa38
	v_readlane_b32 s8, v252, 18
	s_lshr_b32 s4, s2, 2
	v_readlane_b32 s2, v255, 37
	v_readlane_b32 s9, v252, 19
	v_readlane_b32 s10, v252, 20
	v_readlane_b32 s11, v252, 21
	v_readlane_b32 s12, v252, 22
	v_readlane_b32 s13, v252, 23
	v_readlane_b32 s14, v252, 24
	v_readlane_b32 s15, v252, 25
	v_readlane_b32 s16, v252, 26
	v_readlane_b32 s17, v252, 27
	v_readlane_b32 s18, v252, 28
	v_readlane_b32 s19, v252, 29
	v_readlane_b32 s3, v255, 38
	v_readlane_b32 s20, v252, 30
	v_readlane_b32 s21, v252, 31
	v_readlane_b32 s22, v252, 32
	v_readlane_b32 s23, v252, 33
	s_mov_b64 s[8:9], s[12:13]
	s_and_b32 s6, s66, 3
	s_lshl_b64 s[2:3], s[2:3], 18
	s_mov_b64 s[10:11], s[14:15]
	s_mov_b64 s[12:13], s[16:17]
	s_mov_b64 s[14:15], s[18:19]
	s_add_u32 s2, s14, s2
	s_addc_u32 s3, s15, s3
	s_lshl_b32 s5, s6, 16
	s_add_u32 s5, s2, s5
	s_addc_u32 s7, s3, 0
	s_lshl_b32 s42, s4, 6
	s_lshl_b64 s[2:3], s[42:43], 2
	s_add_u32 s2, s5, s2
	s_mov_b32 s5, s43
	s_addc_u32 s3, s7, s3
	s_lshl_b64 s[4:5], s[4:5], 15
	s_add_u32 s4, s83, s4
	s_addc_u32 s5, s97, s5
	s_lshl_b32 s6, s6, 7
	s_add_u32 s4, s4, s6
	s_mov_b64 s[16:17], s[20:21]
	s_mov_b64 s[18:19], s[22:23]
	s_addc_u32 s5, s5, 0
	s_mov_b64 s[6:7], 0

	.amdhsa_kernel _Z10hybrid_fwd6Params
		.amdhsa_group_segment_fixed_size 8192
		.amdhsa_private_segment_fixed_size 0
		.amdhsa_kernarg_size 600
		.amdhsa_user_sgpr_count 2
		.amdhsa_user_sgpr_dispatch_ptr 0
		.amdhsa_user_sgpr_queue_ptr 0
		.amdhsa_user_sgpr_kernarg_segment_ptr 1
		.amdhsa_user_sgpr_dispatch_id 0
		.amdhsa_user_sgpr_kernarg_preload_length 0
		.amdhsa_user_sgpr_kernarg_preload_offset 0
		.amdhsa_user_sgpr_private_segment_size 0
		.amdhsa_uses_dynamic_stack 0
		.amdhsa_enable_private_segment 0
		.amdhsa_system_sgpr_workgroup_id_x 1
		.amdhsa_system_sgpr_workgroup_id_y 0
		.amdhsa_system_sgpr_workgroup_id_z 0
		.amdhsa_system_sgpr_workgroup_info 0
		.amdhsa_system_vgpr_workitem_id 2
		.amdhsa_next_free_vgpr 256
		.amdhsa_next_free_sgpr 100
		.amdhsa_accum_offset 256
		.amdhsa_reserve_vcc 1
		.amdhsa_float_round_mode_32 0
		.amdhsa_float_round_mode_16_64 0
		.amdhsa_float_denorm_mode_32 3
		.amdhsa_float_denorm_mode_16_64 3
		.amdhsa_dx10_clamp 1
		.amdhsa_ieee_mode 1
		.amdhsa_fp16_overflow 0
		.amdhsa_tg_split 0
		.amdhsa_exception_fp_ieee_invalid_op 0
		.amdhsa_exception_fp_denorm_src 0
		.amdhsa_exception_fp_ieee_div_zero 0
		.amdhsa_exception_fp_ieee_overflow 0
		.amdhsa_exception_fp_ieee_underflow 0
		.amdhsa_exception_fp_ieee_inexact 0
		.amdhsa_exception_int_div_zero 0
	.end_amdhsa_kernel

amdhsa.kernels:
  - .agpr_count:     0
    .args:
      - .offset:         0
        .size:           344
        .value_kind:     by_value
      - .offset:         344
        .size:           4
        .value_kind:     hidden_block_count_x
      - .offset:         348
        .size:           4
        .value_kind:     hidden_block_count_y
      - .offset:         352
        .size:           4
        .value_kind:     hidden_block_count_z
      - .offset:         356
        .size:           2
        .value_kind:     hidden_group_size_x
      - .offset:         358
        .size:           2
        .value_kind:     hidden_group_size_y
      - .offset:         360
        .size:           2
        .value_kind:     hidden_group_size_z
      - .offset:         362
        .size:           2
        .value_kind:     hidden_remainder_x
      - .offset:         364
        .size:           2
        .value_kind:     hidden_remainder_y
      - .offset:         366
        .size:           2
        .value_kind:     hidden_remainder_z
      - .offset:         384
        .size:           8
        .value_kind:     hidden_global_offset_x
      - .offset:         392
        .size:           8
        .value_kind:     hidden_global_offset_y
      - .offset:         400
        .size:           8
        .value_kind:     hidden_global_offset_z
      - .offset:         408
        .size:           2
        .value_kind:     hidden_grid_dims
      - .offset:         432
        .size:           8
        .value_kind:     hidden_multigrid_sync_arg
      - .offset:         464
        .size:           4
        .value_kind:     hidden_dynamic_lds_size
    .group_segment_fixed_size: 8192
    .kernarg_segment_align: 8
    .kernarg_segment_size: 600
    .language:       OpenCL C
    .language_version:
      - 2
      - 0
    .max_flat_workgroup_size: 512
    .name:           _Z10hybrid_fwd6Params
    .private_segment_fixed_size: 0
    .sgpr_count:     106
    .sgpr_spill_count: 263
    .symbol:         _Z10hybrid_fwd6Params.kd
    .uniform_work_group_size: 1
    .uses_dynamic_stack: false
    .vgpr_count:     256
    .vgpr_spill_count: 0
    .wavefront_size: 64
